# k32: k31 + attention queue prefetches the next unit's Q/K/V/gate rows into L2 (ticket published through a spare LDS word, two touch loads per wave in the first tile iteration)
# baseline (speedup 1.0000x reference)
; #define LAS __attribute__((address_space(3)))
; __device__ __forceinline__ float lane0(float v) { return __builtin_bit_cast(float, __builtin_amdgcn_readfirstlane(__builtin_bit_cast(int, v))); }
; #define CTL WSP(unsigned, WS_CTL)
; __device__ __forceinline__ void attn_unit(const UnitDesc& u, LAS unsigned char* shm, float qkmax, float thresh) {
;     ...
;     const float ci = -Rown * LOG2E - qkmax;
;     const float kbq0 = Rq0 * LOG2E;
;     const int qabs = u.q0 + wid * 32 + r32;
;     float l_reg = 0.f; f32x16 o[2]; o[0] = f32x16{}; o[1] = f32x16{};
;     float lA = lfb[1], lB = lfb[2], lC = lfb[3];
;     { const float lf = lfb[0]; const float inc = inc4[0]; wsf[lane] = (inc - lf) * LOG2E; carry = lane0(inc);
;       *(LAS u32x4*)kdst = kreg; *(LAS u32x4*)vdst = vreg;
;       asm volatile("" : "+v"(qr[0]), "+v"(qr[1]), "+v"(qr[2]), "+v"(qr[3]));
;       asm volatile("s_waitcnt vmcnt(0)" : "+v"(kA), "+v"(vA), "+v"(kB), "+v"(vB), "+v"(kC), "+v"(vC) :: "memory"); }
;     int slot = 0, tile = NT - 1; bool stop = false;
; __global__ void __launch_bounds__(NTHR, 2) hymba_fwd(Params P) {
;     ...
;             if (tid == 0) { uw[0] = nxt_ui; nxt_ui = atomicAdd(CTL + 64 + 64 * rep, 1u); }
;             asm volatile("s_waitcnt lgkmcnt(0)\n\ts_barrier" ::: "memory");
;             const int ui = __builtin_amdgcn_readfirstlane((int)uw[0]);
.LBB0_772:
	v_lshlrev_b32_e32 v15, 1, v12
	s_lshl_b32 s12, s52, 10
	v_and_b32_e32 v15, 32, v15
	s_add_i32 s13, 0, 0x2000
	v_lshlrev_b32_e32 v142, 2, v136
	v_lshrrev_b32_e32 v12, 2, v12
	s_add_i32 s12, s12, 0
	v_add_u32_e32 v15, s13, v15
	v_and_or_b32 v12, v12, 3, v142
	s_lshl_b32 s13, s52, 9
	v_lshlrev_b32_e32 v12, 6, v12
	s_sub_i32 s53, s12, s13
	v_add_u32_e32 v147, s66, v10
	v_sub_f32_e32 v10, v0, v14
	v_lshl_add_u32 v143, v137, 4, s12
	v_add3_u32 v144, v15, v13, v12
	s_mov_b32 s12, 0xbfb8aa3b
	s_waitcnt lgkmcnt(0)
	v_mul_f32_e32 v146, 0x3fb8aa3b, v11
	v_mul_f32_e32 v10, 0x3fb8aa3b, v10
	v_lshl_add_u32 v11, v137, 2, s53
	v_mov_b32_e32 v14, v1
	v_mov_b32_e32 v15, v1
	v_lshlrev_b32_e32 v16, 10, v136
	v_lshlrev_b32_e32 v17, 4, v135
	v_fma_f32 v112, v21, s12, -v130
	v_mul_f32_e32 v197, 0x3fb8aa3b, v21
	s_mov_b64 s[98:99], 0
	s_mov_b32 s81, 0
	s_nop 0
	v_readfirstlane_b32 s100, v197
	s_nop 3
	v_mov_b32_e32 v197, s100
	ds_write_b32 v11, v10 offset:32768
	v_readfirstlane_b32 s12, v0
	ds_write_b128 v143, v[2:5]
	ds_write_b128 v143, v[6:9] offset:8192
	v_mov_b32_e32 v0, v1
	v_mov_b32_e32 v2, v1
	v_mov_b32_e32 v3, v1
	v_mov_b32_e32 v4, v1
	v_mov_b32_e32 v5, v1
	v_mov_b32_e32 v6, v1
	v_mov_b32_e32 v7, v1
	v_mov_b32_e32 v8, v1
	v_mov_b32_e32 v9, v1
	v_mov_b32_e32 v10, v1
	v_mov_b32_e32 v11, v1
	v_mov_b32_e32 v12, v1
	v_mov_b32_e32 v13, v1
	v_mov_b64_e32 v[48:49], v[14:15]
	v_mov_b64_e32 v[64:65], v[14:15]
	v_mov_b64_e32 v[32:33], v[14:15]
	v_add3_u32 v145, 0, v16, v17
	s_add_i32 s73, s66, s49
	v_mov_b64_e32 v[46:47], v[12:13]
	v_mov_b64_e32 v[44:45], v[10:11]
	v_mov_b64_e32 v[42:43], v[8:9]
	v_mov_b64_e32 v[40:41], v[6:7]
	v_mov_b64_e32 v[38:39], v[4:5]
	v_mov_b64_e32 v[36:37], v[2:3]
	v_mov_b64_e32 v[34:35], v[0:1]
	v_mov_b64_e32 v[62:63], v[12:13]
	v_mov_b64_e32 v[60:61], v[10:11]
	v_mov_b64_e32 v[58:59], v[8:9]
	v_mov_b64_e32 v[56:57], v[6:7]
	v_mov_b64_e32 v[54:55], v[4:5]
	v_mov_b64_e32 v[52:53], v[2:3]
	v_mov_b64_e32 v[50:51], v[0:1]
	v_mov_b64_e32 v[30:31], v[12:13]
	v_mov_b64_e32 v[28:29], v[10:11]
	v_mov_b64_e32 v[26:27], v[8:9]
	v_mov_b64_e32 v[24:25], v[6:7]
	v_mov_b64_e32 v[22:23], v[4:5]
	v_mov_b64_e32 v[20:21], v[2:3]
	v_mov_b64_e32 v[18:19], v[0:1]
	v_mov_b64_e32 v[16:17], v[14:15]
	s_sub_i32 s72, s67, s28
	s_add_i32 s73, s73, 31
	v_mov_b32_e32 v113, v112
	v_mov_b32_e32 v114, v112
	v_mov_b32_e32 v115, v112
	v_mov_b32_e32 v116, v112
	v_mov_b32_e32 v117, v112
	v_mov_b32_e32 v118, v112
	v_mov_b32_e32 v119, v112
	v_mov_b32_e32 v120, v112
	v_mov_b32_e32 v121, v112
	v_mov_b32_e32 v122, v112
	v_mov_b32_e32 v123, v112
	v_mov_b32_e32 v124, v112
	v_mov_b32_e32 v125, v112
	v_mov_b32_e32 v126, v112
	v_mov_b32_e32 v127, v112
	s_lshl_b32 s75, s67, 6
	s_mov_b32 s70, 0
	v_mov_b32_e32 v148, 0
	s_mov_b64 s[62:63], 0
	v_mov_b32_e32 v150, s12
	v_mov_b64_e32 v[14:15], v[12:13]
	v_mov_b64_e32 v[12:13], v[10:11]
	v_mov_b64_e32 v[10:11], v[8:9]
	v_mov_b64_e32 v[8:9], v[6:7]
	v_mov_b64_e32 v[6:7], v[4:5]
	v_mov_b64_e32 v[4:5], v[2:3]
	v_mov_b64_e32 v[2:3], v[0:1]
	s_waitcnt vmcnt(0)
	s_mov_b64 s[82:83], exec
	s_and_b64 exec, exec, s[4:5]
	v_mov_b32_e32 v189, 0x11404
	ds_write_b32 v189, v129
	s_mov_b64 exec, s[82:83]
	s_branch .LBB0_777

; #define LAS __attribute__((address_space(3)))
; template <bool BAND>
; __device__ __forceinline__ void tile_body(f32x16* o, float& l_reg, const bf16x8* qr, const LAS unsigned char* kbs, const LAS float* wb, int vb, float ci, int hi, int keybase, int qabs) {
;     f32x16 p0, p1;
; #pragma unroll
;     for (int g4 = 0; g4 < 4; ++g4) {
;         const f32x4 ba = *(const LAS f32x4*)(wb + 8 * g4 + 4 * hi) + ci, bb = *(const LAS f32x4*)(wb + 32 + 8 * g4 + 4 * hi) + ci;
; #pragma unroll
;         for (int e = 0; e < 4; ++e) { p0[4 * g4 + e] = ba[e]; p1[4 * g4 + e] = bb[e]; }
;     }
; #pragma unroll
;     for (int d0 = 0; d0 < 4; ++d0) {
;         const bf16x8 b0 = *(const LAS bf16x8*)(kbs + d0 * 2048), b1 = *(const LAS bf16x8*)(kbs + d0 * 2048 + 512);
;         p0 = __builtin_amdgcn_mfma_f32_32x32x16_bf16(b0, qr[d0], p0, 0, 0, 0); p1 = __builtin_amdgcn_mfma_f32_32x32x16_bf16(b1, qr[d0], p1, 0, 0, 0); }
.LBB0_783:
	s_andn2_saveexec_b64 s[12:13], s[12:13]
	v_mov_b32_e32 v149, s67
	v_add_f32_e32 v149, s28, v149
	v_add_f32_e32 v149, s66, v149
	s_or_b64 exec, exec, s[12:13]
	v_add_f32_e32 v149, v0, v149
	s_xor_b32 s74, s70, 1
	v_add_f32_e32 v0, v150, v149
	s_lshl_b32 s12, s74, 8
	v_sub_f32_e32 v0, v0, v140
	s_add_i32 s71, s53, s12
	s_lshl_b32 s78, s74, 14
	s_max_i32 s12, s48, 4
	v_mul_f32_e32 v140, 0x3fb8aa3b, v0
	v_lshl_add_u32 v0, v137, 2, s71
	v_readfirstlane_b32 s76, v149
	v_add_u32_e32 v149, s78, v143
	s_add_i32 s28, s12, -4
	ds_write_b32 v0, v140 offset:32768
	ds_write_b128 v149, v[66:69]
	ds_write_b128 v149, v[74:77] offset:8192
	s_lshl_b64 s[12:13], s[28:29], 11
	s_waitcnt lgkmcnt(0)
	v_lshl_add_u64 v[66:67], v[110:111], 0, s[12:13]
	s_lshl_b64 s[12:13], s[28:29], 16
	global_load_dword v140, v[66:67], off
	v_lshl_add_u64 v[74:75], v[106:107], 0, s[12:13]
	global_load_dwordx4 v[66:69], v[74:75], off
	v_cndmask_b32_e64 v74, 0, 1, s[58:59]
	v_lshl_add_u64 v[152:153], v[108:109], 0, s[12:13]
	v_cmp_ne_u32_e64 s[12:13], 1, v74
	global_load_dwordx4 v[74:77], v[152:153], off
	s_cmp_lg_u32 s81, 0
	s_cbranch_scc1 .Lmy_pf_skip
	s_mov_b32 s81, 1
	v_mov_b32_e32 v189, 0x11404
	ds_read_b32 v188, v189
	v_readfirstlane_b32 s100, v208
	s_waitcnt lgkmcnt(0)
	v_readfirstlane_b32 s82, v188
	s_lshr_b32 s100, s100, 6
	s_cmp_lt_u32 s82, 64
	s_cbranch_scc1 .Lmy_pf_skip
	s_cmp_gt_u32 s82, 0x83f
	s_cbranch_scc1 .Lmy_pf_skip
	s_bfe_u32 s83, s82, 0x30003
	s_lshl_b32 s83, s83, 13
	s_lshr_b32 s101, s82, 6
	s_lshl_b32 s101, s101, 8
	s_sub_i32 s101, 0x2000, s101
	s_add_i32 s83, s83, s101
	s_and_b32 s101, s100, 1
	s_lshl_b32 s101, s101, 7
	s_add_i32 s83, s83, s101
	s_lshl_b32 s83, s83, 10
	s_and_b32 s101, s82, 7
	s_lshl_b32 s101, s101, 7
	s_add_i32 s83, s83, s101
	v_lshlrev_b32_e32 v189, 10, v137
	v_add_u32_e32 v189, s83, v189
	s_lshr_b32 s100, s100, 1
	v_readlane_b32 s82, v255, 26
	v_readlane_b32 s83, v255, 27
	s_cmp_lg_u32 s100, 2
	s_cbranch_scc1 .Lmy_pf_notv
	v_readlane_b32 s82, v255, 28
	v_readlane_b32 s83, v255, 29
.Lmy_pf_notv:
	s_cmp_eq_u32 s100, 0
	s_cselect_b64 s[82:83], s[26:27], s[82:83]
	s_cmp_eq_u32 s100, 3
	s_cselect_b64 s[82:83], s[24:25], s[82:83]
	s_nop 0
	global_load_dword v188, v189, s[82:83]
	v_add_u32_e32 v190, 0x10000, v189
	global_load_dword v188, v190, s[82:83]
.Lmy_pf_skip:
	s_andn2_b64 vcc, exec, s[58:59]
	s_cbranch_vccnz .LBB0_792
	s_and_b64 vcc, exec, s[98:99]
	s_cbranch_vccnz .LBB0_792
	s_sub_i32 s28, s75, 64
	s_cmp_gt_i32 s28, s73
	s_cbranch_scc1 .LBB0_792
	s_lshl_b32 s64, s70, 8
	s_lshl_b32 s28, s70, 14
	s_add_i32 s66, s53, s64
	s_cmp_lt_i32 s48, s72
	v_add_u32_e32 v151, s28, v144
	s_mov_b64 s[64:65], -1
	v_add_u32_e32 v152, s28, v145
	v_lshl_add_u32 v153, v142, 2, s66
	s_cbranch_scc1 .LBB0_789
	ds_read_b128 v[34:37], v153 offset:32768
	ds_read_b128 v[38:41], v153 offset:32800
	ds_read_b128 v[42:45], v153 offset:32832
	ds_read_b128 v[46:49], v153 offset:32864
	ds_read_b128 v[50:53], v153 offset:32896
	ds_read_b128 v[54:57], v153 offset:32928
	ds_read_b128 v[58:61], v153 offset:32960
	ds_read_b128 v[62:65], v153 offset:32992
	ds_read_b128 v[154:157], v152
	ds_read_b128 v[158:161], v152 offset:512
	s_waitcnt lgkmcnt(4)
	ds_read_b128 v[210:213], v152 offset:2048
	ds_read_b128 v[214:217], v152 offset:2560
	ds_read_b128 v[218:221], v152 offset:4096
	ds_read_b128 v[222:225], v152 offset:4608
	ds_read_b128 v[226:229], v152 offset:6656
	ds_read_b128 v[230:233], v152 offset:6144
	v_pk_add_f32 v[56:57], v[118:119], v[56:57]
	s_waitcnt lgkmcnt(9)
	v_pk_add_f32 v[60:61], v[122:123], v[60:61]
	s_waitcnt lgkmcnt(8)
	v_pk_add_f32 v[64:65], v[126:127], v[64:65]
	v_pk_add_f32 v[52:53], v[114:115], v[52:53]
	v_pk_add_f32 v[62:63], v[124:125], v[62:63]
	v_pk_add_f32 v[58:59], v[120:121], v[58:59]
	v_pk_add_f32 v[54:55], v[116:117], v[54:55]
	v_pk_add_f32 v[50:51], v[112:113], v[50:51]
	v_pk_add_f32 v[48:49], v[126:127], v[48:49]
	v_pk_add_f32 v[44:45], v[122:123], v[44:45]
	v_pk_add_f32 v[40:41], v[118:119], v[40:41]
	v_pk_add_f32 v[36:37], v[114:115], v[36:37]
	v_pk_add_f32 v[46:47], v[124:125], v[46:47]
	v_pk_add_f32 v[42:43], v[120:121], v[42:43]
	v_pk_add_f32 v[38:39], v[116:117], v[38:39]
	v_pk_add_f32 v[34:35], v[112:113], v[34:35]
	s_waitcnt lgkmcnt(6)
	v_mfma_f32_32x32x16_bf16 v[50:65], v[158:161], v[94:97], v[50:65]
	v_mfma_f32_32x32x16_bf16 v[34:49], v[154:157], v[94:97], v[34:49]
	s_waitcnt lgkmcnt(4)
	v_mfma_f32_32x32x16_bf16 v[50:65], v[214:217], v[98:101], v[50:65]
	v_mfma_f32_32x32x16_bf16 v[34:49], v[210:213], v[98:101], v[34:49]
	s_waitcnt lgkmcnt(2)
	v_mfma_f32_32x32x16_bf16 v[50:65], v[222:225], v[102:105], v[50:65]
	v_mfma_f32_32x32x16_bf16 v[34:49], v[218:221], v[102:105], v[34:49]
	s_waitcnt lgkmcnt(1)
	v_mfma_f32_32x32x16_bf16 v[50:65], v[226:229], v[90:93], v[50:65]
	v_add_u32_e32 v154, s75, v142
	v_subrev_u32_e32 v156, 32, v154
	v_subrev_u32_e32 v155, 64, v154
	v_cmp_le_i32_e32 vcc, v156, v147
	s_waitcnt lgkmcnt(0)
; __device__ __forceinline__ void pv(f32x16* o, int vb, bf16x8 pa0, bf16x8 pa1, bf16x8 pa2, bf16x8 pa3) {
; #pragma unroll
;     for (int d0 = 0; d0 < 2; ++d0) { s16x4 lo[4], hi[4];
; #pragma unroll
;         for (int ks = 0; ks < 4; ++ks) {
;             asm volatile("ds_read_b64_tr_b16 %0,%1 offset:%c2" : "=&v"(lo[ks]) : "v"(vb), "i"(d0 * 4096 + ks * 1024) : "memory");
;             asm volatile("ds_read_b64_tr_b16 %0,%1 offset:%c2" : "=&v"(hi[ks]) : "v"(vb), "i"(d0 * 4096 + ks * 1024 + 512) : "memory"); }
;         asm volatile("s_waitcnt lgkmcnt(0)" ::: "memory"); __builtin_amdgcn_sched_barrier(0);
;     ...
;         o[d0] = __builtin_amdgcn_mfma_f32_32x32x16_bf16(pa0, PK(0), o[d0], 0, 0, 0);
;         o[d0] = __builtin_amdgcn_mfma_f32_32x32x16_bf16(pa1, PK(1), o[d0], 0, 0, 0);
;         o[d0] = __builtin_amdgcn_mfma_f32_32x32x16_bf16(pa2, PK(2), o[d0], 0, 0, 0);
;         o[d0] = __builtin_amdgcn_mfma_f32_32x32x16_bf16(pa3, PK(3), o[d0], 0, 0, 0);
; template <bool BAND>
; __device__ __forceinline__ void tile_body(f32x16* o, float& l_reg, const bf16x8* qr, const LAS unsigned char* kbs, const LAS float* wb, int vb, float ci, int hi, int keybase, int qabs) {
;     ...
;     if (BAND) {
; #pragma unroll
;         for (int r = 0; r < 16; ++r) { const int key = keybase + 8 * (r >> 2) + (r & 3); if (key > qabs) p0[r] = -INFINITY; if (key + 32 > qabs) p1[r] = -INFINITY; }
;     }
;     f32x2 s2 = {0.f, 0.f};
; #pragma unroll
;     for (int r = 0; r < 16; r += 2) {
;         p0[r] = __builtin_amdgcn_exp2f(p0[r]); p0[r + 1] = __builtin_amdgcn_exp2f(p0[r + 1]); p1[r] = __builtin_amdgcn_exp2f(p1[r]); p1[r + 1] = __builtin_amdgcn_exp2f(p1[r + 1]);
;         s2 += (f32x2){p0[r], p0[r + 1]}; s2 += (f32x2){p1[r], p1[r + 1]}; }
;     l_reg += s2.x + s2.y;
;     u32x4 pw0, pw1, pw2, pw3;
;     pw0 = (u32x4){cvtpk(p0[0], p0[1]), cvtpk(p0[2], p0[3]), cvtpk(p0[4], p0[5]), cvtpk(p0[6], p0[7])};
;     pw1 = (u32x4){cvtpk(p0[8], p0[9]), cvtpk(p0[10], p0[11]), cvtpk(p0[12], p0[13]), cvtpk(p0[14], p0[15])};
;     pw2 = (u32x4){cvtpk(p1[0], p1[1]), cvtpk(p1[2], p1[3]), cvtpk(p1[4], p1[5]), cvtpk(p1[6], p1[7])};
;     pw3 = (u32x4){cvtpk(p1[8], p1[9]), cvtpk(p1[10], p1[11]), cvtpk(p1[12], p1[13]), cvtpk(p1[14], p1[15])};
;     pv(o, vb, __builtin_bit_cast(bf16x8, pw0), __builtin_bit_cast(bf16x8, pw1), __builtin_bit_cast(bf16x8, pw2), __builtin_bit_cast(bf16x8, pw3));
	v_mfma_f32_32x32x16_bf16 v[34:49], v[230:233], v[90:93], v[34:49]
	s_nop 5
	v_cndmask_b32_e32 v50, v134, v50, vcc
	v_cmp_lt_i32_e32 vcc, v155, v147
	s_nop 3
	v_cndmask_b32_e32 v35, v134, v35, vcc
	v_cmp_le_i32_e32 vcc, v155, v147
	v_subrev_u32_e32 v155, 31, v154
	v_exp_f32_e32 v35, v35
	v_cndmask_b32_e32 v34, v134, v34, vcc
	v_cmp_le_i32_e32 vcc, v155, v147
	v_subrev_u32_e32 v155, 62, v154
	v_exp_f32_e32 v34, v34
	v_cndmask_b32_e32 v51, v134, v51, vcc
	v_cmp_le_i32_e32 vcc, v155, v147
	s_nop 1
	v_cndmask_b32_e32 v155, v134, v36, vcc
	v_subrev_u32_e32 v36, 30, v154
	v_cmp_le_i32_e32 vcc, v36, v147
	v_subrev_u32_e32 v36, 61, v154
	s_nop 0
	v_cndmask_b32_e32 v52, v134, v52, vcc
	v_cmp_le_i32_e32 vcc, v36, v147
	v_subrev_u32_e32 v36, 29, v154
	s_nop 0
	v_cndmask_b32_e32 v156, v134, v37, vcc
	v_cmp_le_i32_e32 vcc, v36, v147
	v_subrev_u32_e32 v36, 56, v154
	v_exp_f32_e32 v37, v51
	v_cndmask_b32_e32 v53, v134, v53, vcc
	v_cmp_le_i32_e32 vcc, v36, v147
	v_subrev_u32_e32 v36, 24, v154
	s_nop 0
	v_cndmask_b32_e32 v157, v134, v38, vcc
	v_cmp_le_i32_e32 vcc, v36, v147
	v_subrev_u32_e32 v36, 55, v154
	v_exp_f32_e32 v38, v155
	v_cndmask_b32_e32 v54, v134, v54, vcc
	v_cmp_le_i32_e32 vcc, v36, v147
	v_subrev_u32_e32 v36, 23, v154
	s_nop 0
	v_cndmask_b32_e32 v158, v134, v39, vcc
	v_cmp_le_i32_e32 vcc, v36, v147
	v_subrev_u32_e32 v36, 54, v154
	v_exp_f32_e32 v39, v156
	v_cndmask_b32_e32 v55, v134, v55, vcc
	v_cmp_le_i32_e32 vcc, v36, v147
	v_subrev_u32_e32 v36, 22, v154
	v_cvt_pk_bf16_f32 v156, v34, v35
	v_cndmask_b32_e32 v159, v134, v40, vcc
	v_cmp_le_i32_e32 vcc, v36, v147
	v_subrev_u32_e32 v36, 53, v154
	v_exp_f32_e32 v40, v52
	v_cndmask_b32_e32 v56, v134, v56, vcc
	v_cmp_le_i32_e32 vcc, v36, v147
	v_subrev_u32_e32 v36, 21, v154
	s_nop 0
	v_cndmask_b32_e32 v160, v134, v41, vcc
	v_cmp_le_i32_e32 vcc, v36, v147
	v_subrev_u32_e32 v36, 48, v154
	v_exp_f32_e32 v41, v53
	v_cndmask_b32_e32 v57, v134, v57, vcc
	v_cmp_le_i32_e32 vcc, v36, v147
	v_add_u32_e32 v36, -16, v154
	v_exp_f32_e32 v51, v57
	v_cndmask_b32_e32 v161, v134, v42, vcc
	v_cmp_le_i32_e32 vcc, v36, v147
	v_subrev_u32_e32 v36, 47, v154
	v_exp_f32_e32 v52, v161
	v_cndmask_b32_e32 v58, v134, v58, vcc
	v_cmp_le_i32_e32 vcc, v36, v147
	v_add_u32_e32 v36, -15, v154
	s_nop 0
	v_cndmask_b32_e32 v162, v134, v43, vcc
	v_cmp_le_i32_e32 vcc, v36, v147
	v_subrev_u32_e32 v36, 46, v154
	v_pk_add_f32 v[42:43], v[34:35], 0 op_sel_hi:[1,0]
	v_cndmask_b32_e32 v59, v134, v59, vcc
	v_cmp_le_i32_e32 vcc, v36, v147
	v_add_u32_e32 v36, -14, v154
	v_exp_f32_e32 v53, v162
	v_cndmask_b32_e32 v163, v134, v44, vcc
	v_cmp_le_i32_e32 vcc, v36, v147
	v_subrev_u32_e32 v36, 45, v154
	v_exp_f32_e32 v44, v157
	v_cndmask_b32_e32 v60, v134, v60, vcc
	v_cmp_le_i32_e32 vcc, v36, v147
	v_add_u32_e32 v36, -13, v154
	v_cvt_pk_bf16_f32 v157, v38, v39
	v_cndmask_b32_e32 v164, v134, v45, vcc
	v_cmp_le_i32_e32 vcc, v36, v147
	v_subrev_u32_e32 v36, 40, v154
	v_exp_f32_e32 v45, v158
	v_cndmask_b32_e32 v61, v134, v61, vcc
	v_cmp_le_i32_e32 vcc, v36, v147
	v_add_u32_e32 v36, -8, v154
	v_exp_f32_e32 v57, v164
	v_cndmask_b32_e32 v165, v134, v46, vcc
	v_cmp_le_i32_e32 vcc, v36, v147
	v_subrev_u32_e32 v36, 39, v154
	v_exp_f32_e32 v46, v54
	v_cndmask_b32_e32 v62, v134, v62, vcc
	v_cmp_le_i32_e32 vcc, v36, v147
	v_add_u32_e32 v36, -7, v154
	v_exp_f32_e32 v54, v58
	v_cndmask_b32_e32 v166, v134, v47, vcc
	v_cmp_le_i32_e32 vcc, v36, v147
	v_subrev_u32_e32 v36, 38, v154
	v_exp_f32_e32 v47, v55
	v_cndmask_b32_e32 v63, v134, v63, vcc
	v_cmp_le_i32_e32 vcc, v36, v147
	v_add_u32_e32 v36, -6, v154
	v_exp_f32_e32 v55, v59
	v_cndmask_b32_e32 v167, v134, v48, vcc
	v_cmp_le_i32_e32 vcc, v36, v147
	v_subrev_u32_e32 v36, 37, v154
	v_exp_f32_e32 v48, v159
	v_cndmask_b32_e32 v168, v134, v64, vcc
	v_cmp_le_i32_e32 vcc, v36, v147
	v_add_u32_e32 v36, -5, v154
	v_exp_f32_e32 v58, v60
	v_cndmask_b32_e32 v169, v134, v49, vcc
	v_cmp_le_i32_e32 vcc, v36, v147
	v_exp_f32_e32 v36, v50
	v_exp_f32_e32 v49, v160
	v_exp_f32_e32 v50, v56
	v_exp_f32_e32 v56, v163
	v_pk_add_f32 v[42:43], v[36:37], v[42:43]
	v_exp_f32_e32 v59, v61
	v_pk_add_f32 v[42:43], v[38:39], v[42:43]
	v_exp_f32_e32 v64, v167
	v_pk_add_f32 v[42:43], v[40:41], v[42:43]
	v_cvt_pk_bf16_f32 v167, v50, v51
	v_pk_add_f32 v[42:43], v[44:45], v[42:43]
	v_exp_f32_e32 v60, v165
	v_pk_add_f32 v[42:43], v[46:47], v[42:43]
	v_exp_f32_e32 v61, v166
	v_pk_add_f32 v[42:43], v[48:49], v[42:43]
	v_cvt_pk_bf16_f32 v160, v52, v53
	v_pk_add_f32 v[42:43], v[50:51], v[42:43]
	ds_read_b64_tr_b16 v[50:51],v151 offset:0
	v_exp_f32_e32 v62, v62
	v_pk_add_f32 v[42:43], v[52:53], v[42:43]
	ds_read_b64_tr_b16 v[52:53],v151 offset:512
	v_exp_f32_e32 v63, v63
	v_pk_add_f32 v[42:43], v[54:55], v[42:43]
	v_exp_f32_e32 v172, v168
	v_cvt_pk_bf16_f32 v168, v54, v55
	ds_read_b64_tr_b16 v[54:55],v151 offset:1024
	v_cndmask_b32_e32 v154, v134, v65, vcc
	v_pk_add_f32 v[42:43], v[56:57], v[42:43]
	v_exp_f32_e32 v65, v169
	v_cvt_pk_bf16_f32 v161, v56, v57
	ds_read_b64_tr_b16 v[56:57],v151 offset:1536
	v_pk_add_f32 v[42:43], v[58:59], v[42:43]
	v_exp_f32_e32 v173, v154
	v_cvt_pk_bf16_f32 v169, v58, v59
	ds_read_b64_tr_b16 v[58:59],v151 offset:2048
	v_pk_add_f32 v[42:43], v[60:61], v[42:43]
	v_cvt_pk_bf16_f32 v162, v60, v61
	ds_read_b64_tr_b16 v[60:61],v151 offset:2560
	v_pk_add_f32 v[42:43], v[62:63], v[42:43]
	v_cvt_pk_bf16_f32 v170, v62, v63
	ds_read_b64_tr_b16 v[62:63],v151 offset:3072
	v_pk_add_f32 v[42:43], v[64:65], v[42:43]
	v_cvt_pk_bf16_f32 v163, v64, v65
	ds_read_b64_tr_b16 v[64:65],v151 offset:3584
	v_pk_add_f32 v[42:43], v[172:173], v[42:43]
	s_waitcnt lgkmcnt(0)
	v_cvt_pk_bf16_f32 v158, v44, v45
	v_add_f32_e32 v42, v42, v43
	v_add_f32_e32 v154, v148, v42
	v_cvt_pk_bf16_f32 v159, v48, v49
	v_cvt_pk_bf16_f32 v164, v36, v37
	v_cvt_pk_bf16_f32 v165, v40, v41
	v_cvt_pk_bf16_f32 v166, v46, v47
	v_cvt_pk_bf16_f32 v171, v172, v173
	v_mfma_f32_32x32x16_bf16 v[2:17], v[156:159], v[50:53], v[2:17]
	ds_read_b64_tr_b16 v[172:173],v151 offset:4096
	ds_read_b64_tr_b16 v[174:175],v151 offset:4608
	ds_read_b64_tr_b16 v[176:177],v151 offset:5120
	ds_read_b64_tr_b16 v[178:179],v151 offset:5632
	ds_read_b64_tr_b16 v[180:181],v151 offset:6144
	ds_read_b64_tr_b16 v[182:183],v151 offset:6656
	ds_read_b64_tr_b16 v[184:185],v151 offset:7168
	v_mfma_f32_32x32x16_bf16 v[2:17], v[160:163], v[54:57], v[2:17]
	ds_read_b64_tr_b16 v[186:187],v151 offset:7680
	s_waitcnt lgkmcnt(0)
	v_mfma_f32_32x32x16_bf16 v[2:17], v[164:167], v[58:61], v[2:17]
	v_mfma_f32_32x32x16_bf16 v[2:17], v[168:171], v[62:65], v[2:17]
	v_mfma_f32_32x32x16_bf16 v[18:33], v[156:159], v[172:175], v[18:33]
	s_mov_b64 s[64:65], 0
	v_mfma_f32_32x32x16_bf16 v[18:33], v[160:163], v[176:179], v[18:33]
	v_mfma_f32_32x32x16_bf16 v[18:33], v[164:167], v[180:183], v[18:33]
	v_mfma_f32_32x32x16_bf16 v[18:33], v[168:171], v[184:187], v[18:33]
